# waves 4-7 keep the raised priority through the GEMM tile epilogue as well (reset when the tile loop of the phase ends)
# speedup vs baseline: 1.0048x; 1.0048x over previous
.LBB0_623:
	s_setprio 0
	s_and_b64 vcc, exec, s[10:11]
	s_cbranch_vccz .LBB0_628
	v_readlane_b32 s2, v254, 3
	v_readlane_b32 s3, v255, 39
	s_add_i32 s8, s3, s2
	s_mul_i32 s34, s8, 0xb00
	s_lshl_b64 s[2:3], s[34:35], 1
	v_readlane_b32 s4, v255, 30
	v_readlane_b32 s5, v255, 31
	s_add_u32 s2, s4, s2
	s_addc_u32 s3, s5, s3
	v_readlane_b32 s5, v254, 4
	v_mov_b32_e32 v170, v163
	s_mul_i32 s4, s5, 0x1600
	v_readlane_b32 s6, v255, 32
	v_readlane_b32 s7, v255, 33
	v_ashrrev_i32_e32 v0, 6, v170
	s_waitcnt vmcnt(3)
	v_and_b32_e32 v2, 63, v170
	s_add_u32 s4, s6, s4
	s_mul_hi_i32 s5, s5, 0x1600
	s_waitcnt vmcnt(2)
	v_bfe_u32 v7, v170, 3, 3
	v_bfe_u32 v171, v170, 4, 2
	s_addc_u32 s5, s7, s5
	v_readlane_b32 s9, v255, 9
	v_lshlrev_b32_e32 v173, 4, v2
	v_lshl_or_b32 v2, v0, 5, v7
	v_xor_b32_e32 v4, v171, v170
	s_movk_i32 s24, 0xb00
	s_add_u32 s6, s2, s9
	v_mad_i64_i32 v[2:3], s[14:15], v2, s24, 0
	v_lshlrev_b32_e32 v4, 3, v4
	v_lshlrev_b32_e32 v174, 12, v0
	s_addc_u32 s7, s3, 0
	v_lshlrev_b64 v[164:165], 1, v[2:3]
	v_and_b32_e32 v4, 56, v4
	v_or_b32_e32 v8, v173, v174
	v_lshlrev_b32_e32 v6, 2, v0
	s_add_u32 s10, s4, s9
	v_lshl_add_u64 v[2:3], s[6:7], 0, v[164:165]
	s_waitcnt vmcnt(0)
	v_lshlrev_b32_e32 v130, 1, v4
	v_mov_b32_e32 v131, v1
	v_readfirstlane_b32 s9, v8
	v_add_u32_e32 v0, 0x8000, v8
	s_addc_u32 s11, s5, 0
	v_lshl_add_u64 v[2:3], v[2:3], 0, v[130:131]
	s_mov_b32 m0, s9
	v_readfirstlane_b32 s9, v0
	v_or_b32_e32 v0, 1, v6
	v_lshl_add_u64 v[4:5], s[10:11], 0, v[164:165]
	global_load_lds_dwordx4 v[2:3], off
	v_lshl_or_b32 v2, v0, 3, v7
	v_lshl_add_u64 v[4:5], v[4:5], 0, v[130:131]
	s_mov_b32 m0, s9
	v_lshrrev_b32_e32 v3, 1, v2
	global_load_lds_dwordx4 v[4:5], off
	v_xor_b32_e32 v4, v3, v170
	v_mad_i64_i32 v[2:3], s[14:15], v2, s24, 0
	v_lshlrev_b32_e32 v4, 3, v4
	v_lshlrev_b32_e32 v175, 10, v0
	v_lshlrev_b64 v[168:169], 1, v[2:3]
	v_and_b32_e32 v4, 56, v4
	v_or_b32_e32 v9, v173, v175
	v_lshl_add_u64 v[2:3], s[6:7], 0, v[168:169]
	v_lshlrev_b32_e32 v132, 1, v4
	v_mov_b32_e32 v133, v1
	v_readfirstlane_b32 s9, v9
	v_add_u32_e32 v0, 0x8000, v9
	v_or_b32_e32 v10, 2, v6
	v_lshl_add_u64 v[2:3], v[2:3], 0, v[132:133]
	v_lshl_add_u64 v[4:5], s[10:11], 0, v[168:169]
	s_mov_b32 m0, s9
	v_readfirstlane_b32 s9, v0
	v_lshl_or_b32 v0, v10, 3, v7
	v_lshl_add_u64 v[4:5], v[4:5], 0, v[132:133]
	global_load_lds_dwordx4 v[2:3], off
	s_mov_b32 m0, s9
	v_lshrrev_b32_e32 v2, 1, v0
	global_load_lds_dwordx4 v[4:5], off
	v_xor_b32_e32 v4, v2, v170
	v_mad_i64_i32 v[2:3], s[14:15], v0, s24, 0
	v_lshlrev_b32_e32 v0, 3, v4
	v_lshlrev_b32_e32 v176, 10, v10
	v_lshlrev_b64 v[154:155], 1, v[2:3]
	v_and_b32_e32 v0, 56, v0
	v_or_b32_e32 v10, v173, v176
	v_lshl_add_u64 v[2:3], s[6:7], 0, v[154:155]
	v_lshlrev_b32_e32 v0, 1, v0
	v_readfirstlane_b32 s9, v10
	v_lshl_add_u64 v[2:3], v[2:3], 0, v[0:1]
	s_mov_b32 m0, s9
	v_or_b32_e32 v6, 3, v6
	global_load_lds_dwordx4 v[2:3], off
	v_add_u32_e32 v2, 0x8000, v10
	v_lshl_add_u64 v[4:5], s[10:11], 0, v[154:155]
	v_readfirstlane_b32 s9, v2
	v_lshl_or_b32 v2, v6, 3, v7
	v_lshl_add_u64 v[4:5], v[4:5], 0, v[0:1]
	s_mov_b32 m0, s9
	v_lshrrev_b32_e32 v3, 1, v2
	global_load_lds_dwordx4 v[4:5], off
	v_xor_b32_e32 v4, v3, v170
	v_mad_i64_i32 v[2:3], s[14:15], v2, s24, 0
	v_lshlrev_b32_e32 v4, 3, v4
	v_lshlrev_b32_e32 v177, 10, v6
	v_lshlrev_b64 v[156:157], 1, v[2:3]
	v_and_b32_e32 v4, 56, v4
	v_or_b32_e32 v6, v173, v177
	v_lshl_add_u64 v[2:3], s[6:7], 0, v[156:157]
	v_lshlrev_b32_e32 v158, 1, v4
	v_mov_b32_e32 v159, v1
	v_readfirstlane_b32 s6, v6
	v_lshl_add_u64 v[2:3], v[2:3], 0, v[158:159]
	v_lshl_add_u64 v[4:5], s[10:11], 0, v[156:157]
	s_mov_b32 m0, s6
	v_readlane_b32 s10, v255, 10
	global_load_lds_dwordx4 v[2:3], off
	v_add_u32_e32 v2, 0x8000, v6
	v_readlane_b32 s11, v255, 11
	v_readfirstlane_b32 s6, v2
	v_lshl_add_u64 v[2:3], s[2:3], 0, v[164:165]
	s_mov_b32 s11, s35
	v_add_u32_e32 v6, 0x10000, v8
	v_lshl_add_u64 v[4:5], v[4:5], 0, v[158:159]
	s_mov_b32 m0, s6
	v_lshl_add_u64 v[2:3], v[2:3], 0, s[10:11]
	v_readfirstlane_b32 s6, v6
	global_load_lds_dwordx4 v[4:5], off
	v_lshl_add_u64 v[2:3], v[2:3], 0, v[130:131]
	s_mov_b32 m0, s6
	v_mov_b32_e32 v123, 0
	v_mov_b32_e32 v124, 0
	v_mov_b32_e32 v125, 0
	v_mov_b32_e32 v126, 0
	v_mov_b32_e32 v127, 0
	v_mov_b32_e32 v128, 0
	v_mov_b32_e32 v129, 0
	v_mov_b32_e32 v118, 0
	v_mov_b32_e32 v119, 0
	v_mov_b32_e32 v120, 0
	v_mov_b32_e32 v121, 0
	v_mov_b32_e32 v114, 0
	v_mov_b32_e32 v115, 0
	v_mov_b32_e32 v116, 0
	v_mov_b32_e32 v117, 0
	v_mov_b32_e32 v110, 0
	v_mov_b32_e32 v111, 0
	v_mov_b32_e32 v112, 0
	v_mov_b32_e32 v113, 0
	v_mov_b32_e32 v106, 0
	v_mov_b32_e32 v107, 0
	v_mov_b32_e32 v108, 0
	v_mov_b32_e32 v109, 0
	v_mov_b32_e32 v102, 0
	v_mov_b32_e32 v103, 0
	v_mov_b32_e32 v104, 0
	v_mov_b32_e32 v105, 0
	v_mov_b32_e32 v98, 0
	v_mov_b32_e32 v99, 0
	v_mov_b32_e32 v100, 0
	v_mov_b32_e32 v101, 0
	v_mov_b32_e32 v94, 0
	v_mov_b32_e32 v95, 0
	v_mov_b32_e32 v96, 0
	v_mov_b32_e32 v97, 0
	v_mov_b32_e32 v90, 0
	v_mov_b32_e32 v91, 0
	v_mov_b32_e32 v92, 0
	v_mov_b32_e32 v93, 0
	v_mov_b32_e32 v86, 0
	v_mov_b32_e32 v87, 0
	v_mov_b32_e32 v88, 0
	v_mov_b32_e32 v89, 0
	v_mov_b32_e32 v82, 0
	v_mov_b32_e32 v83, 0
	v_mov_b32_e32 v84, 0
	v_mov_b32_e32 v85, 0
	v_mov_b32_e32 v78, 0
	v_mov_b32_e32 v79, 0
	v_mov_b32_e32 v80, 0
	v_mov_b32_e32 v81, 0
	v_mov_b32_e32 v74, 0
	v_mov_b32_e32 v75, 0
	v_mov_b32_e32 v76, 0
	v_mov_b32_e32 v77, 0
	v_mov_b32_e32 v70, 0
	v_mov_b32_e32 v71, 0
	v_mov_b32_e32 v72, 0
	v_mov_b32_e32 v73, 0
	v_mov_b32_e32 v66, 0
	v_mov_b32_e32 v67, 0
	v_mov_b32_e32 v68, 0
	v_mov_b32_e32 v69, 0
	v_mov_b32_e32 v62, 0
	v_mov_b32_e32 v63, 0
	v_mov_b32_e32 v64, 0
	v_mov_b32_e32 v65, 0
	v_mov_b32_e32 v58, 0
	v_mov_b32_e32 v59, 0
	v_mov_b32_e32 v60, 0
	v_mov_b32_e32 v61, 0
	v_mov_b32_e32 v54, 0
	v_mov_b32_e32 v55, 0
	v_mov_b32_e32 v56, 0
	v_mov_b32_e32 v57, 0
	v_mov_b32_e32 v50, 0
	v_mov_b32_e32 v51, 0
	v_mov_b32_e32 v52, 0
	v_mov_b32_e32 v53, 0
	v_mov_b32_e32 v46, 0
	v_mov_b32_e32 v47, 0
	v_mov_b32_e32 v48, 0
	v_mov_b32_e32 v49, 0
	v_mov_b32_e32 v38, 0
	v_mov_b32_e32 v39, 0
	v_mov_b32_e32 v40, 0
	v_mov_b32_e32 v41, 0
	v_mov_b32_e32 v26, 0
	v_mov_b32_e32 v27, 0
	v_mov_b32_e32 v28, 0
	v_mov_b32_e32 v29, 0
	v_mov_b32_e32 v18, 0
	v_mov_b32_e32 v19, 0
	v_mov_b32_e32 v20, 0
	v_mov_b32_e32 v21, 0
	v_mov_b32_e32 v42, 0
	v_mov_b32_e32 v43, 0
	v_mov_b32_e32 v44, 0
	v_mov_b32_e32 v45, 0
	v_mov_b32_e32 v34, 0
	v_mov_b32_e32 v35, 0
	v_mov_b32_e32 v36, 0
	v_mov_b32_e32 v37, 0
	v_mov_b32_e32 v30, 0
	v_mov_b32_e32 v31, 0
	v_mov_b32_e32 v32, 0
	v_mov_b32_e32 v33, 0
	v_mov_b32_e32 v22, 0
	v_mov_b32_e32 v23, 0
	v_mov_b32_e32 v24, 0
	v_mov_b32_e32 v25, 0
	v_mov_b32_e32 v14, 0
	v_mov_b32_e32 v15, 0
	v_mov_b32_e32 v16, 0
	v_mov_b32_e32 v17, 0
	v_mov_b32_e32 v12, 0
	v_mov_b32_e32 v13, 0
	s_waitcnt vmcnt(0)
	s_waitcnt vmcnt(0) lgkmcnt(0)
	s_barrier
	global_load_lds_dwordx4 v[2:3], off
	v_add_u32_e32 v2, 0x18000, v8
	v_lshl_add_u64 v[4:5], s[4:5], 0, v[164:165]
	v_readfirstlane_b32 s6, v2
	s_mov_b32 m0, s6
	s_mov_b32 s6, s10
	v_lshl_add_u64 v[4:5], v[4:5], 0, s[10:11]
	v_lshl_add_u64 v[2:3], s[2:3], 0, v[168:169]
	v_writelane_b32 v255, s6, 10
	v_add_u32_e32 v6, 0x10000, v9
	v_lshl_add_u64 v[4:5], v[4:5], 0, v[130:131]
	v_lshl_add_u64 v[2:3], v[2:3], 0, s[10:11]
	v_writelane_b32 v255, s7, 11
	v_readfirstlane_b32 s6, v6
	global_load_lds_dwordx4 v[4:5], off
	v_lshl_add_u64 v[2:3], v[2:3], 0, v[132:133]
	s_mov_b32 m0, s6
	v_lshl_add_u64 v[4:5], s[4:5], 0, v[168:169]
	global_load_lds_dwordx4 v[2:3], off
	v_add_u32_e32 v2, 0x18000, v9
	v_lshl_add_u64 v[4:5], v[4:5], 0, s[10:11]
	v_readfirstlane_b32 s6, v2
	v_lshl_add_u64 v[4:5], v[4:5], 0, v[132:133]
	s_mov_b32 m0, s6
	v_and_b32_e32 v134, 15, v170
	global_load_lds_dwordx4 v[4:5], off
	v_ashrrev_i32_e32 v2, 1, v170
	s_movk_i32 s6, 0xff80
	v_and_or_b32 v172, v2, s6, v134
	v_readlane_b32 s6, v254, 6
	v_mov_b32_e32 v5, 0
	v_readlane_b32 s7, v254, 7
	s_andn2_b64 vcc, exec, s[6:7]
	s_cbranch_vccnz .Lgemm_skip_zero_b
	v_lshrrev_b32_e32 v10, 1, v134
	v_lshlrev_b32_e32 v2, 7, v170
	v_and_b32_e32 v179, 0x6780, v2
	v_xor_b32_e32 v2, v171, v10
	v_lshlrev_b32_e32 v178, 7, v172
	v_lshlrev_b32_e32 v180, 4, v2
	v_or_b32_e32 v11, v178, v180
	ds_read_b128 v[146:149], v11 offset:2048
	ds_read_b128 v[150:153], v11
	v_or_b32_e32 v11, v179, v180
	v_lshl_add_u64 v[2:3], s[4:5], 0, v[132:133]
	v_lshl_add_u64 v[4:5], s[2:3], 0, v[132:133]
	v_lshl_add_u64 v[6:7], s[4:5], 0, v[130:131]
	v_lshl_add_u64 v[8:9], s[2:3], 0, v[130:131]
	ds_read_b128 v[130:133], v11 offset:38912
	ds_read_b128 v[134:137], v11 offset:36864
	ds_read_b128 v[138:141], v11 offset:34816
	ds_read_b128 v[142:145], v11 offset:32768
	v_bitop3_b32 v10, v171, v10, 4 bitop3:0x36
	v_mov_b32_e32 v122, 0
	v_lshlrev_b32_e32 v181, 4, v10
	v_lshl_add_u64 v[160:161], v[8:9], 0, v[164:165]
	v_lshl_add_u64 v[164:165], v[6:7], 0, v[164:165]
	v_lshl_add_u64 v[166:167], v[4:5], 0, v[168:169]
	v_lshl_add_u64 v[168:169], v[2:3], 0, v[168:169]
	s_mov_b32 s9, 0
	v_readlane_b32 s6, v254, 5
	v_mov_b32_e32 v10, v122
	v_mov_b32_e32 v11, v122
	v_mov_b32_e32 v6, v122
	v_mov_b32_e32 v7, v122
	v_mov_b32_e32 v8, v122
	v_mov_b32_e32 v9, v122
	v_mov_b32_e32 v2, v122
	v_mov_b32_e32 v3, v122
	v_mov_b32_e32 v4, v122
	v_mov_b32_e32 v5, v122
	v_readlane_b32 s31, v254, 8
	v_readlane_b32 s38, v254, 9
